# r13 + MLA unit prologue de-serialised: the wait between the first and second K/V tile loads moved below the second tile's loads
# speedup vs baseline: 1.0113x; 1.0113x over previous
.LBB0_262:
	s_lshl_b32 s9, s2, 8
	s_add_i32 s10, s52, s9
	s_ashr_i32 s11, s10, 31
	s_mul_i32 s28, s10, 0x600
	s_mul_hi_i32 s2, s10, 0x600
	s_add_u32 s30, s18, s28
	s_addc_u32 s31, s19, s2
	s_mul_i32 s2, s8, 0x60
	s_lshl_b64 s[28:29], s[2:3], 1
	v_add_lshl_u32 v0, s9, v192, 4
	s_add_u32 s28, s30, s28
	v_ashrrev_i32_e32 v1, 31, v0
	s_addc_u32 s29, s31, s29
	s_ashr_i32 s53, s52, 31
	v_lshlrev_b64 v[0:1], 2, v[0:1]
	s_lshl_b64 s[72:73], s[52:53], 11
	v_lshl_add_u64 v[8:9], v[162:163], 0, v[0:1]
	v_lshl_add_u64 v[4:5], v[164:165], 0, v[0:1]
	s_add_u32 s2, s20, s72
	global_load_dwordx4 v[0:3], v[4:5], off offset:16
	global_load_dwordx4 v[16:19], v[4:5], off
	s_nop 0
	global_load_dwordx4 v[4:7], v[8:9], off offset:16
	global_load_dwordx4 v[20:23], v[8:9], off
	v_lshl_add_u64 v[8:9], s[28:29], 0, v[148:149]
	s_addc_u32 s9, s21, s73
	s_lshl_b32 s28, s8, 8
	s_add_u32 s76, s2, s28
	s_addc_u32 s77, s9, 0
	s_lshl_b64 s[74:75], s[52:53], 6
	s_add_u32 s52, s22, s74
	s_addc_u32 s53, s23, s75
	v_mov_b32_e32 v181, v151
	v_mov_b32_e32 v179, v151
	v_lshl_add_u64 v[24:25], s[76:77], 0, v[154:155]
	v_lshlrev_b32_e32 v150, 1, v152
	v_lshl_add_u64 v[32:33], s[52:53], 0, v[180:181]
	v_mov_b32_e32 v183, v151
	v_lshl_add_u64 v[36:37], v[8:9], 0, v[178:179]
	v_lshl_add_u64 v[28:29], v[24:25], 0, v[150:151]
	s_waitcnt lgkmcnt(0)
	v_lshl_add_u64 v[44:45], v[32:33], 0, v[182:183]
	global_load_dwordx4 v[8:11], v[36:37], off offset:128
	global_load_dwordx4 v[12:15], v[36:37], off offset:160
	global_load_dwordx4 v[116:119], v[36:37], off
	global_load_dwordx4 v[112:115], v[36:37], off offset:32
	global_load_dwordx4 v[24:27], v[28:29], off offset:128
	s_nop 0
	global_load_dwordx4 v[28:31], v[28:29], off
	s_nop 0
	global_load_dwordx4 v[32:35], v[44:45], off
	global_load_dwordx4 v[124:127], v[36:37], off offset:64
	global_load_dwordx4 v[120:123], v[36:37], off offset:96
	v_lshl_add_u64 v[36:37], s[76:77], 0, v[156:157]
	v_lshl_add_u64 v[40:41], v[36:37], 0, v[150:151]
	global_load_dwordx4 v[36:39], v[40:41], off offset:128
	s_nop 0
	global_load_dwordx4 v[40:43], v[40:41], off
	v_add_co_u32_e32 v48, vcc, s24, v44
	v_add_u32_e32 v64, 0, v193
	s_nop 0
	v_addc_co_u32_e32 v49, vcc, 0, v45, vcc
	global_load_dwordx4 v[50:53], v[48:49], off offset:-4096
	s_waitcnt vmcnt(0)
	v_add_u32_e32 v65, 0, v194
	s_mov_b32 s52, 0
	s_mov_b32 s53, s52
	s_mov_b32 s9, s3
	s_mov_b32 s54, s52
	s_mov_b32 s55, s52
	s_mov_b32 s56, s52
	s_mov_b32 s57, s52
	s_mov_b32 s58, s52
	s_mov_b32 s59, s52
	s_mov_b32 s60, s52
	s_mov_b32 s61, s52
	s_mov_b32 s62, s52
	s_mov_b32 s63, s52
	s_mov_b32 s64, s52
	s_mov_b32 s65, s52
	s_mov_b32 s66, s52
	s_mov_b32 s67, s52
	s_lshl_b64 s[30:31], s[8:9], 8
	s_add_u32 s30, s30, s72
	s_addc_u32 s31, s31, s73
	s_mov_b32 s28, 1
	s_mov_b32 s2, 2
	v_lshl_add_u64 v[184:185], v[166:167], 0, s[74:75]
	v_lshl_add_u64 v[186:187], s[30:31], 0, v[168:169]
	v_mov_b32_e32 v171, 0
	v_mov_b32_e32 v175, 1.0
	s_mov_b32 s9, 2
	s_waitcnt vmcnt(7)
	ds_write_b128 v196, v[24:27]
	s_waitcnt vmcnt(6)
	ds_write_b128 v64, v[28:31] offset:24576
	s_waitcnt vmcnt(5)
	ds_write_b128 v65, v[32:35] offset:24576
	v_mov_b32_e32 v44, v16
	v_mov_b32_e32 v47, v16
	v_mov_b32_e32 v16, v21
	v_and_b32_e32 v61, 0xffff0000, v8
	v_and_b32_e32 v60, 0xffff0000, v12
	v_mov_b32_e32 v45, v20
	v_mov_b32_e32 v46, v20
	v_mov_b32_e32 v20, v17
	v_pk_mul_f32 v[16:17], v[16:17], v[60:61]
	s_waitcnt lgkmcnt(0)
	v_add_f32_e32 v67, v16, v17
	s_barrier
	s_waitcnt vmcnt(0)
	s_waitcnt vmcnt(2)
	ds_write_b128 v196, v[36:39] offset:8192
	s_waitcnt vmcnt(1)
	ds_write_b128 v64, v[40:43] offset:40960
	v_add_u32_e32 v16, 0, v198
	ds_read_b128 v[24:27], v16 offset:24576
	v_mov_b32_e32 v54, v18
	v_mov_b32_e32 v55, v22
	v_mov_b32_e32 v56, v22
	v_mov_b32_e32 v57, v18
	v_lshlrev_b32_e32 v59, 16, v8
	v_lshlrev_b32_e32 v58, 16, v12
	v_lshlrev_b32_e32 v63, 16, v9
	v_lshlrev_b32_e32 v62, 16, v13
	v_and_b32_e32 v9, 0xffff0000, v9
	v_pk_mul_f32 v[44:45], v[44:45], v[58:59]
	v_pk_mul_f32 v[46:47], v[46:47], v[58:59]
	v_pk_mul_f32 v[54:55], v[54:55], v[62:63]
	v_pk_mul_f32 v[56:57], v[56:57], v[62:63]
	v_and_b32_e32 v8, 0xffff0000, v13
	v_mov_b32_e32 v22, v19
	v_mov_b32_e32 v18, v23
	v_add_u32_e32 v58, 0, v199
	v_sub_f32_e32 v68, v55, v54
	v_add_f32_e32 v69, v56, v57
	v_pk_mul_f32 v[12:13], v[22:23], v[8:9]
	v_pk_mul_f32 v[8:9], v[18:19], v[8:9]
	ds_read_b128 v[54:57], v58 offset:24576
	ds_read_b128 v[16:19], v16 offset:32768
	v_sub_f32_e32 v62, v45, v44
	v_add_f32_e32 v63, v46, v47
	s_waitcnt lgkmcnt(2)
	v_mfma_f32_32x32x16_bf16 v[32:47], v[24:27], v[116:119], 0
	v_sub_f32_e32 v64, v13, v12
	v_add_f32_e32 v70, v8, v9
	v_lshlrev_b32_e32 v9, 16, v10
	v_lshlrev_b32_e32 v8, 16, v14
	v_mov_b32_e32 v12, v0
	v_mov_b32_e32 v13, v4
	v_pk_mul_f32 v[12:13], v[12:13], v[8:9]
	v_pk_mul_f32 v[20:21], v[20:21], v[60:61]
	v_sub_f32_e32 v71, v13, v12
	v_mov_b32_e32 v12, v4
	v_mov_b32_e32 v13, v0
	ds_read_b128 v[58:61], v58 offset:32768
	v_sub_f32_e32 v66, v21, v20
	s_waitcnt lgkmcnt(1)
	v_mfma_f32_32x32x16_bf16 v[16:31], v[16:19], v[116:119], 0
	v_mul_f32_e64 v8, v12, v8
	v_mul_f32_e64 v9, v13, v9
	v_mov_b32_e32 v4, v1
	v_add_f32_e32 v72, v8, v9
	v_and_b32_e32 v9, 0xffff0000, v10
	v_add_u32_e32 v10, 0, v200
	v_and_b32_e32 v8, 0xffff0000, v14
	v_mov_b32_e32 v0, v5
	v_mfma_f32_32x32x16_bf16 v[32:47], v[54:57], v[112:115], v[32:47]
	ds_read_b128 v[54:57], v10 offset:24576
	v_mul_f32_e64 v12, v4, v8
	v_mul_f32_e64 v13, v5, v9
	v_mul_f32_e64 v0, v0, v8
	v_mul_f32_e64 v1, v1, v9
	v_sub_f32_e32 v12, v13, v12
	v_add_f32_e32 v13, v0, v1
	v_lshlrev_b32_e32 v1, 16, v11
	v_lshlrev_b32_e32 v0, 16, v15
	s_waitcnt lgkmcnt(1)
	v_mfma_f32_32x32x16_bf16 v[16:31], v[58:61], v[112:115], v[16:31]
	v_mov_b32_e32 v4, v2
	v_mov_b32_e32 v5, v6
	ds_read_b128 v[58:61], v10 offset:32768
	v_mul_f32_e64 v4, v4, v0
	v_mul_f32_e64 v5, v5, v1
	global_load_dwordx4 v[144:147], v[48:49], off
	v_sub_f32_e32 v14, v5, v4
	v_mov_b32_e32 v5, v2
	v_add_u32_e32 v2, 0, v201
	s_waitcnt lgkmcnt(1)
	v_mfma_f32_32x32x16_bf16 v[32:47], v[54:57], v[124:127], v[32:47]
	ds_read_b128 v[54:57], v2 offset:24576
	v_mov_b32_e32 v4, v6
	v_mul_f32_e64 v0, v4, v0
	v_mul_f32_e64 v1, v5, v1
	v_mov_b32_e32 v6, v3
	v_lshl_add_u64 v[48:49], s[76:77], 0, v[158:159]
	s_waitcnt vmcnt(1)
	ds_write_b128 v65, v[50:53] offset:40960
	v_lshl_add_u64 v[48:49], v[48:49], 0, v[150:151]
	s_waitcnt lgkmcnt(2)
	v_mfma_f32_32x32x16_bf16 v[16:31], v[58:61], v[124:127], v[16:31]
	v_add_f32_e32 v58, v0, v1
	v_and_b32_e32 v1, 0xffff0000, v11
	v_and_b32_e32 v0, 0xffff0000, v15
	ds_read_b128 v[8:11], v2 offset:32768
	v_mov_b32_e32 v2, v7
	v_pk_mul_f32 v[4:5], v[6:7], v[0:1]
	v_pk_mul_f32 v[0:1], v[2:3], v[0:1]
	v_add_u32_e32 v6, 0, v202
	v_sub_f32_e32 v4, v5, v4
	v_add_f32_e32 v5, v0, v1
	ds_read_b128 v[0:3], v6 offset:24576
	s_waitcnt lgkmcnt(3)
	v_mfma_f32_32x32x16_bf16 v[32:47], v[54:57], v[120:123], v[32:47]
	v_cvt_pk_bf16_f32 v132, v62, v66
	v_cvt_pk_bf16_f32 v133, v68, v64
	v_cvt_pk_bf16_f32 v134, v71, v12
	v_cvt_pk_bf16_f32 v135, v14, v4
	v_cvt_pk_bf16_f32 v131, v58, v5
	ds_read_b128 v[4:7], v6 offset:32768
	v_cvt_pk_bf16_f32 v128, v63, v67
	s_waitcnt lgkmcnt(2)
	v_mfma_f32_32x32x16_bf16 v[16:31], v[8:11], v[120:123], v[16:31]
	v_add_u32_e32 v8, 0, v203
	ds_read_b128 v[50:53], v8 offset:32768
	v_cvt_pk_bf16_f32 v129, v69, v70
	v_cvt_pk_bf16_f32 v130, v72, v13
	s_waitcnt lgkmcnt(2)
	v_mfma_f32_32x32x16_bf16 v[32:47], v[0:3], v[132:135], v[32:47]
	ds_read_b128 v[0:3], v8 offset:24576
	global_load_dwordx4 v[140:143], v[48:49], off
	global_load_dwordx4 v[136:139], v[48:49], off offset:128
	s_waitcnt lgkmcnt(2)
	v_mfma_f32_32x32x16_bf16 v[16:31], v[4:7], v[132:135], v[16:31]
	s_waitcnt lgkmcnt(0)
	v_mfma_f32_32x32x16_bf16 v[32:47], v[0:3], v[128:131], v[32:47]
	v_mov_b64_e32 v[0:1], s[52:53]
	v_mov_b64_e32 v[14:15], s[66:67]
	v_mov_b64_e32 v[2:3], s[54:55]
	v_mov_b64_e32 v[4:5], s[56:57]
	v_mov_b64_e32 v[6:7], s[58:59]
	v_mov_b64_e32 v[8:9], s[60:61]
	v_mov_b64_e32 v[10:11], s[62:63]
	v_mfma_f32_32x32x16_bf16 v[16:31], v[50:53], v[128:131], v[16:31]
	s_nop 3
	v_max_f32_e32 v50, v33, v33
	v_max_f32_e32 v51, v32, v32
	v_max_f32_e32 v50, v51, v50
	v_max3_f32 v50, v50, v34, v35
	v_max3_f32 v50, v50, v36, v37
	v_max3_f32 v50, v50, v38, v39
	v_max3_f32 v50, v50, v40, v41
	v_max3_f32 v50, v50, v42, v43
	v_max3_f32 v50, v50, v44, v45
	v_max3_f32 v50, v50, v46, v47
	v_max3_f32 v50, v50, v16, v17
	v_max3_f32 v50, v50, v18, v19
	v_max3_f32 v50, v50, v20, v21
	v_max3_f32 v50, v50, v22, v23
	v_max3_f32 v50, v50, v24, v25
	v_max3_f32 v50, v50, v26, v27
	v_max3_f32 v50, v50, v28, v29
	v_max3_f32 v50, v50, v30, v31
	v_mov_b32_e32 v51, v50
	s_nop 1
	v_permlane32_swap_b32_e32 v50, v51
	v_max_f32_e32 v48, v51, v51
	v_max_f32_e32 v49, v50, v50
	v_max_f32_e32 v48, v49, v48
	v_sub_f32_e32 v32, v32, v48
	v_exp_f32_e32 v215, v32
	v_sub_f32_e32 v32, v33, v48
	v_exp_f32_e32 v219, v32
	v_sub_f32_e32 v32, v34, v48
	v_exp_f32_e32 v216, v32
	v_sub_f32_e32 v32, v35, v48
	v_exp_f32_e32 v220, v32
	v_sub_f32_e32 v32, v36, v48
	v_exp_f32_e32 v217, v32
	v_sub_f32_e32 v32, v37, v48
	v_exp_f32_e32 v221, v32
	v_sub_f32_e32 v32, v38, v48
	v_exp_f32_e32 v218, v32
	v_sub_f32_e32 v32, v39, v48
	v_exp_f32_e32 v222, v32
	v_sub_f32_e32 v32, v40, v48
	v_exp_f32_e32 v188, v32
	v_sub_f32_e32 v32, v41, v48
	v_exp_f32_e32 v211, v32
	v_sub_f32_e32 v32, v42, v48
	v_exp_f32_e32 v189, v32
	v_sub_f32_e32 v32, v43, v48
	v_exp_f32_e32 v212, v32
	v_sub_f32_e32 v32, v44, v48
	v_exp_f32_e32 v190, v32
	v_sub_f32_e32 v32, v45, v48
	v_exp_f32_e32 v213, v32
	v_sub_f32_e32 v32, v46, v48
	v_exp_f32_e32 v191, v32
	v_sub_f32_e32 v32, v47, v48
	v_exp_f32_e32 v214, v32
	v_mov_b64_e32 v[12:13], s[64:65]
	v_sub_f32_e32 v79, v31, v48
	v_sub_f32_e32 v78, v30, v48
	v_sub_f32_e32 v77, v29, v48
	v_sub_f32_e32 v76, v28, v48
	v_sub_f32_e32 v75, v27, v48
	v_sub_f32_e32 v74, v26, v48
	v_sub_f32_e32 v73, v25, v48
	v_sub_f32_e32 v72, v24, v48
	v_sub_f32_e32 v71, v23, v48
	v_sub_f32_e32 v70, v22, v48
	v_sub_f32_e32 v69, v21, v48
	v_sub_f32_e32 v68, v20, v48
	v_sub_f32_e32 v67, v19, v48
	v_sub_f32_e32 v66, v18, v48
	v_sub_f32_e32 v65, v17, v48
	v_sub_f32_e32 v64, v16, v48
	v_sub_f32_e32 v48, 0, v48
	v_mov_b64_e32 v[30:31], v[14:15]
	v_mov_b64_e32 v[28:29], v[12:13]
	v_mov_b64_e32 v[26:27], v[10:11]
	v_mov_b64_e32 v[24:25], v[8:9]
	v_mov_b64_e32 v[22:23], v[6:7]
	v_mov_b64_e32 v[20:21], v[4:5]
	v_mov_b64_e32 v[18:19], v[2:3]
	v_mov_b64_e32 v[16:17], v[0:1]
	v_mov_b32_e32 v49, v48
	v_mov_b32_e32 v50, v48
	v_mov_b32_e32 v51, v48
	v_mov_b32_e32 v52, v48
	v_mov_b32_e32 v53, v48
	v_mov_b32_e32 v54, v48
	v_mov_b32_e32 v55, v48
	v_mov_b32_e32 v56, v48
	v_mov_b32_e32 v57, v48
	v_mov_b32_e32 v58, v48
	v_mov_b32_e32 v59, v48
	v_mov_b32_e32 v60, v48
	v_mov_b32_e32 v61, v48
	v_mov_b32_e32 v62, v48
	v_mov_b32_e32 v63, v48
